# one static s_setprio 1 for waves 0-3 during the MLA unit body (reset to 0 at the unit end)
# speedup vs baseline: 1.0124x; 1.0124x over previous
; #define LAS __attribute__((address_space(3)))
; #define GAS __attribute__((address_space(1)))
; __device__ __forceinline__ void attn_unit(const bf16_t* Qh, const bf16_t* Kh, const bf16_t* Vh, bf16_t* Oh  , int S, int qb, LAS unsigned char* lds, int tid) {
;     const int lane = tid & 63, r32 = lane & 31, hi = lane >> 5; const int wid = __builtin_amdgcn_readfirstlane(tid >> 6);
;     const int qrow = qb * 512 + wid * 64 + r32;
;     const bf16_t* Qw = Qh + (size_t)qrow * 96 + 8 * hi;
;     LAS unsigned char* ql = lds + QOFF + wid * 12288 + lane * 16;
; #pragma unroll
;     for (int s = 0; s < 6; ++s) { *(LAS bf16x8*)(ql + s * 1024) = GLD(bf16x8, Qw + 16 * s); *(LAS bf16x8*)(ql + (6 + s) * 1024) = GLD(bf16x8, Qw + 32 * 96 + 16 * s); }
;     const bool has1 = tid < 256; const int kc0 = tid, kc1 = has1 ? tid + 512 : tid;
;     const unsigned kd0 = (unsigned)((kc0 / 12) * KPITCH + (kc0 % 12) * 16);
;     const unsigned kd1 = has1 ? (unsigned)((kc1 / 12) * KPITCH + (kc1 % 12) * 16) : (unsigned)(DUMMY + (tid - 256) * 16);
;     const unsigned kd1n = has1 ? BUF : 0u;
;     const unsigned vd = (unsigned)(KBYTES + ((tid & 7) >> 2) * 4096 + (tid >> 3) * 64 + (tid & 3) * 16);
;     const GAS u32x4* Kg = (const GAS u32x4*)Kh; const GAS u32x4* Vg = (const GAS u32x4*)Vh;
;     const int NT = S >> 6;
;     u32x4 ka = GLD(u32x4, Kg + kc0), kb = GLD(u32x4, Kg + kc1), va = GLD(u32x4, Vg + tid);
;     *(LAS u32x4*)(lds + kd0) = ka; *(LAS u32x4*)(lds + kd1) = kb; *(LAS u32x4*)(lds + vd) = va;
;     __syncthreads();
;     f32x16 oa0 = {}, oa1 = {}, ob0 = {}, ob1 = {}; float ma = 0.f, la = 0.f, mb = 0.f, lb = 0.f;
;     const unsigned kfo = (unsigned)(r32 * KPITCH + hi * 16);
;     const unsigned vb = (unsigned)(KBYTES + ((lane >> 4) & 1) * 32 + (lane & 3) * 8 + (4 * hi + ((lane & 15) >> 2)) * 64);
; __global__ void __launch_bounds__(512, 2) fwd_kernel(Args args) {
;     ...
;                 for (int uidx = vcu; uidx < nunits; uidx += G) { const int pair = uidx / nqb, qb = uidx - pair * nqb; const int seq = pair >> 4, head = pair & 15;
;                     const size_t hb = (size_t)pair << P.Sshift;
;                     mla::attn_unit(Qb + hb * 96, KFb + hb * 96, Vb + hb * 64, OAb + ((size_t)seq << P.Sshift) * D + head * 64, P.S, qb, lds, tid); }
.LBB0_76:
	s_abs_i32 s1, s24
	s_mul_hi_u32 s4, s1, s19
	s_mul_i32 s16, s4, s13
	s_sub_i32 s1, s1, s16
	s_ashr_i32 s0, s24, 31
	s_add_i32 s16, s4, 1
	s_sub_i32 s17, s1, s13
	s_cmp_ge_u32 s1, s13
	s_cselect_b32 s4, s16, s4
	s_cselect_b32 s1, s17, s1
	s_add_i32 s16, s4, 1
	s_cmp_ge_u32 s1, s13
	s_cselect_b32 s1, s16, s4
	s_xor_b32 s1, s1, s0
	s_sub_i32 s0, s1, s0
	s_mul_i32 s1, s0, s13
	s_sub_i32 s4, s24, s1
	s_ashr_i32 s1, s0, 31
	s_lshl_b64 s[26:27], s[0:1], s82
	s_mul_i32 s1, s27, 0xc0
	s_mul_hi_u32 s16, s26, 0xc0
	s_add_i32 s1, s16, s1
	s_mul_i32 s16, s26, 0xc0
	s_add_u32 s40, s96, s16
	s_addc_u32 s41, s97, s1
	s_add_u32 s16, s84, s16
	s_addc_u32 s17, s85, s1
	s_lshl_b64 s[26:27], s[26:27], 7
	s_add_u32 s26, s86, s26
	v_readfirstlane_b32 s1, v172
	s_addc_u32 s27, s87, s27
	s_lshl_b32 s4, s4, 9
	s_and_b32 s25, s1, 0xffffffc0
	s_add_i32 s4, s4, s25
	v_or_b32_e32 v136, s4, v148
	v_mov_b64_e32 v[0:1], s[40:41]
	v_mad_i64_i32 v[0:1], s[40:41], v136, s75, v[0:1]
	v_lshl_add_u64 v[40:41], v[0:1], 0, v[168:169]
	v_add_co_u32_e32 v44, vcc, s33, v40
	v_lshlrev_b64 v[60:61], 4, v[172:173]
	s_nop 0
	v_addc_co_u32_e32 v45, vcc, 0, v41, vcc
	v_lshl_add_u64 v[48:49], s[16:17], 0, v[60:61]
	global_load_dwordx4 v[0:3], v[40:41], off
	global_load_dwordx4 v[4:7], v[40:41], off offset:32
	global_load_dwordx4 v[8:11], v[40:41], off offset:64
	global_load_dwordx4 v[12:15], v[44:45], off offset:2080
	global_load_dwordx4 v[16:19], v[44:45], off offset:2112
	global_load_dwordx4 v[20:23], v[40:41], off offset:96
	global_load_dwordx4 v[24:27], v[40:41], off offset:128
	global_load_dwordx4 v[28:31], v[44:45], off offset:2144
	global_load_dwordx4 v[32:35], v[44:45], off offset:2176
	global_load_dwordx4 v[36:39], v[44:45], off offset:2048
	s_nop 0
	global_load_dwordx4 v[40:43], v[40:41], off offset:160
	s_nop 0
	global_load_dwordx4 v[44:47], v[44:45], off offset:2208
	s_nop 0
	global_load_dwordx4 v[48:51], v[48:49], off
	v_lshlrev_b64 v[62:63], 4, v[132:133]
	v_lshl_add_u64 v[52:53], s[16:17], 0, v[62:63]
	global_load_dwordx4 v[52:55], v[52:53], off
	v_lshl_add_u64 v[138:139], s[26:27], 0, v[60:61]
	global_load_dwordx4 v[56:59], v[138:139], off
	s_lshr_b32 s1, s1, 6
	s_mulk_i32 s1, 0x3000
	v_add_u32_e32 v135, s1, v149
	v_add_u32_e32 v163, 0, v150
	v_add_u32_e32 v162, 0, v157
	s_add_u32 s26, s16, 0x3000
	s_movk_i32 s1, 0x2000
	s_addc_u32 s27, s17, 0
	v_ashrrev_i32_e32 v137, 31, v136
	s_waitcnt vmcnt(0)
	ds_write_b128 v135, v[0:3] offset:43008
	s_waitcnt vmcnt(13)
	ds_write_b128 v135, v[4:7] offset:44032
	s_waitcnt vmcnt(12)
	ds_write_b128 v135, v[8:11] offset:45056
	s_waitcnt vmcnt(9)
	ds_write_b128 v135, v[20:23] offset:46080
	s_waitcnt vmcnt(8)
	ds_write_b128 v135, v[24:27] offset:47104
	s_waitcnt vmcnt(5)
	ds_write_b128 v135, v[36:39] offset:49152
	ds_write_b128 v135, v[12:15] offset:50176
	ds_write_b128 v135, v[16:19] offset:51200
	ds_write_b128 v135, v[28:31] offset:52224
	ds_write_b128 v135, v[32:35] offset:53248
	s_waitcnt vmcnt(4)
	ds_write_b128 v135, v[40:43] offset:48128
	s_waitcnt vmcnt(3)
	ds_write_b128 v135, v[44:47] offset:54272
	s_waitcnt vmcnt(2)
	ds_write_b128 v163, v[48:51]
	s_waitcnt vmcnt(1)
	ds_write_b128 v156, v[52:55]
	s_waitcnt vmcnt(0)
	ds_write_b128 v162, v[56:59] offset:13312
	s_waitcnt lgkmcnt(0)
	s_barrier
	v_mov_b64_e32 v[0:1], 0
	v_mov_b64_e32 v[2:3], 0
	v_mov_b64_e32 v[4:5], 0
	v_mov_b64_e32 v[6:7], 0
	v_mov_b64_e32 v[8:9], 0
	v_mov_b64_e32 v[10:11], 0
	v_mov_b64_e32 v[12:13], 0
	v_mov_b64_e32 v[14:15], 0
	v_mov_b64_e32 v[16:17], 0
	v_mov_b64_e32 v[18:19], 0
	v_mov_b64_e32 v[20:21], 0
	v_mov_b64_e32 v[22:23], 0
	v_mov_b64_e32 v[24:25], 0
	v_mov_b64_e32 v[26:27], 0
	v_mov_b64_e32 v[28:29], 0
	v_mov_b64_e32 v[30:31], 0
	v_mov_b64_e32 v[32:33], 0
	v_mov_b64_e32 v[34:35], 0
	v_mov_b64_e32 v[36:37], 0
	v_mov_b64_e32 v[38:39], 0
	v_mov_b64_e32 v[40:41], 0
	v_mov_b64_e32 v[42:43], 0
	v_mov_b64_e32 v[44:45], 0
	v_mov_b64_e32 v[46:47], 0
	v_mov_b64_e32 v[48:49], 0
	v_mov_b64_e32 v[50:51], 0
	v_mov_b64_e32 v[52:53], 0
	v_mov_b64_e32 v[54:55], 0
	v_mov_b64_e32 v[56:57], 0
	v_mov_b64_e32 v[58:59], 0
	v_mov_b64_e32 v[60:61], 0
	v_mov_b64_e32 v[62:63], 0
	v_mov_b32_e32 v140, 0
	v_mov_b32_e32 v141, 0
	v_lshlrev_b32_e32 v171, 4, v172
	v_lshlrev_b32_e32 v184, 4, v132
	v_lshlrev_b32_e32 v146, 4, v174
	v_readfirstlane_b32 s100, v138
	v_readfirstlane_b32 s101, v139
	s_add_u32 s26, s16, 0x3000
	s_addc_u32 s27, s17, 0
	s_mov_b32 s1, 1
	v_readfirstlane_b32 s4, v172
	s_nop 3
	s_cmp_ge_u32 s4, 0x100
	s_cbranch_scc1 .Lmla_prio
	s_setprio 1
